# ffn_fixup loop: the other seven conv weight/bias slices of an iteration touched early (throw-away loads) so the serialized loads hit L1
# speedup vs baseline: 1.0038x; 1.0038x over previous
; __device__ __forceinline__ float bf2f(unsigned short b) { return __uint_as_float((unsigned)b << 16); }
; __device__ __forceinline__ float fast_exp2(float x) { return __builtin_amdgcn_exp2f(x); }
; __device__ __forceinline__ float fast_rcp(float x) { return __builtin_amdgcn_rcpf(x); }
; __device__ __forceinline__ void ffn_fixup(const Params& P, int layer) {
;     ...
;     for (int it = blockIdx.x * 512 + threadIdx.x; it < 512 * 2 * CG; it += gridDim.x * 512) {
;         const int cgi = it % CG, e = (it / CG) & 1, chunk = it / (2 * CG), col = cgi * 8;
;         const bf16_t *up, *mid, *dn; bool zu = false, zd = false;
;         if (e == 0) { zu = (chunk % 32) == 0; up = UB + ((size_t)(zu ? chunk : chunk - 1) * 4 + 3) * NUP; mid = UB + ((size_t)chunk * 4 + 0) * NUP; dn = UB + ((size_t)chunk * 4 + 1) * NUP; }
;         else { zd = (chunk % 32) == 31; up = UB + ((size_t)chunk * 4 + 2) * NUP; mid = UB + ((size_t)chunk * 4 + 3) * NUP; dn = UB + ((size_t)(zd ? chunk : chunk + 1) * 4 + 0) * NUP; }
;         const float fu = zu ? 0.f : 1.f, fd = zd ? 0.f : 1.f;
;         float res[8];
;         bf16_t ug[8], mg[8], dg[8], uv[8], mv[8], dv[8];
;         *(u32x4*)ug = *(const u32x4*)(up + col); *(u32x4*)mg = *(const u32x4*)(mid + col); *(u32x4*)dg = *(const u32x4*)(dn + col);
;         *(u32x4*)uv = *(const u32x4*)(up + DFF + col); *(u32x4*)mv = *(const u32x4*)(mid + DFF + col); *(u32x4*)dv = *(const u32x4*)(dn + DFF + col);
; #pragma unroll
;         for (int k = 0; k < 8; ++k) {
;             const int cg_ = col + k, cv_ = DFF + col + k;
;             const float gt = cw[cg_] * bf2f(ug[k]) * fu + cw[NUP + cg_] * bf2f(mg[k]) + cw[2 * NUP + cg_] * bf2f(dg[k]) * fd + cb[cg_];
;             const float vl = cw[cv_] * bf2f(uv[k]) * fu + cw[NUP + cv_] * bf2f(mv[k]) + cw[2 * NUP + cv_] * bf2f(dv[k]) * fd + cb[cv_];
;             res[k] = gt * fast_rcp(1.f + fast_exp2(-LOG2E * gt)) * vl;
;         }
.LBB0_861:
	s_or_b64 exec, exec, s[14:15]
	v_mul_i32_i24_e32 v0, 0x160, v0
	v_lshlrev_b32_e32 v0, 3, v0
	v_sub_u32_e32 v62, v59, v0
	v_ashrrev_i32_e32 v63, 31, v62
	v_lshlrev_b64 v[56:57], 1, v[62:63]
	v_lshl_add_u64 v[2:3], v[2:3], 0, v[56:57]
	s_movk_i32 s4, 0x1000
	global_load_dwordx4 v[22:25], v[2:3], off
	v_add_co_u32_e32 v2, vcc, s4, v2
	v_lshl_add_u64 v[4:5], v[4:5], 0, v[56:57]
	s_nop 0
	v_addc_co_u32_e32 v3, vcc, 0, v3, vcc
	global_load_dwordx4 v[10:13], v[2:3], off offset:1536
	v_add_co_u32_e32 v2, vcc, s4, v4
	v_lshl_add_u64 v[26:27], v[6:7], 0, v[56:57]
	s_nop 0
	v_addc_co_u32_e32 v3, vcc, 0, v5, vcc
	global_load_dwordx4 v[18:21], v[4:5], off
	global_load_dwordx4 v[6:9], v[2:3], off offset:1536
	v_add_co_u32_e32 v2, vcc, s4, v26
	global_load_dwordx4 v[14:17], v[26:27], off
	s_nop 0
	v_addc_co_u32_e32 v3, vcc, 0, v27, vcc
	global_load_dwordx4 v[2:5], v[2:3], off offset:1536
	v_add_u32_e32 v0, 0xb00, v62
	v_lshlrev_b64 v[26:27], 2, v[62:63]
	v_lshl_add_u64 v[34:35], s[62:63], 0, v[26:27]
	v_lshl_add_u64 v[42:43], s[76:77], 0, v[26:27]
	v_lshlrev_b64 v[26:27], 2, v[0:1]
	v_lshl_add_u64 v[44:45], s[62:63], 0, v[26:27]
	v_lshl_add_u64 v[64:65], s[76:77], 0, v[26:27]
	global_load_dwordx4 v[26:29], v[34:35], off offset:16
	global_load_dwordx4 v[48:51], v[34:35], off
	s_mov_b64 s[4:5], 0x5800
	v_lshl_add_u64 v[30:31], v[34:35], 0, s[4:5]
	v_lshl_add_u64 v[116:117], v[44:45], 0, s[4:5]
	s_mov_b64 s[4:5], 0xb000
	v_lshl_add_u64 v[36:37], v[34:35], 0, s[4:5]
	v_lshl_add_u64 v[118:119], v[44:45], 0, s[4:5]
	global_load_dwordx4 v[84:87], v[30:31], off
	global_load_dwordx4 v[88:91], v[36:37], off
	global_load_dwordx4 v[92:95], v[42:43], off
	global_load_dwordx4 v[96:99], v[44:45], off
	global_load_dwordx4 v[100:103], v[116:117], off
	global_load_dwordx4 v[104:107], v[118:119], off
	global_load_dwordx4 v[108:111], v[64:65], off
	s_movk_i32 s4, 0x5000
	s_mov_b32 s5, 0xb000
	s_waitcnt vmcnt(14)
	v_and_b32_e32 v33, 0xffff0000, v22
	v_lshlrev_b32_e32 v32, 16, v22
	s_waitcnt vmcnt(12)
	v_and_b32_e32 v41, 0xffff0000, v18
	v_lshlrev_b32_e32 v40, 16, v18
	s_waitcnt vmcnt(7)
	v_pk_mul_f32 v[38:39], v[48:49], v[32:33]
	v_add_co_u32_e32 v32, vcc, s4, v34
	s_nop 1
	v_addc_co_u32_e32 v33, vcc, 0, v35, vcc
	global_load_dwordx4 v[52:55], v[32:33], off offset:2048
	s_nop 0
	global_load_dwordx4 v[30:33], v[30:31], off offset:16
	v_add_co_u32_e32 v34, vcc, s5, v34
	s_waitcnt vmcnt(1)
	v_pk_mul_f32 v[40:41], v[52:53], v[40:41]
	v_addc_co_u32_e32 v35, vcc, 0, v35, vcc
	global_load_dwordx4 v[68:71], v[34:35], off
	s_nop 0
	global_load_dwordx4 v[34:37], v[36:37], off offset:16
	v_pk_fma_f32 v[38:39], v[60:61], v[38:39], v[40:41] op_sel_hi:[0,1,1]
	v_and_b32_e32 v41, 0xffff0000, v14
	v_lshlrev_b32_e32 v40, 16, v14
	s_waitcnt vmcnt(1)
	v_pk_mul_f32 v[40:41], v[68:69], v[40:41]
	s_nop 0
	v_pk_fma_f32 v[46:47], v[58:59], v[40:41], v[38:39] op_sel_hi:[0,1,1]
	global_load_dwordx4 v[38:41], v[42:43], off offset:16
	global_load_dwordx4 v[72:75], v[42:43], off
	v_and_b32_e32 v43, 0xffff0000, v10
	v_lshlrev_b32_e32 v42, 16, v10
	s_waitcnt vmcnt(0)
	v_pk_add_f32 v[52:53], v[72:73], v[46:47]
	v_add_co_u32_e32 v72, vcc, s4, v44
	global_load_dwordx4 v[46:49], v[44:45], off offset:16
	global_load_dwordx4 v[76:79], v[44:45], off
	v_addc_co_u32_e32 v73, vcc, 0, v45, vcc
	global_load_dwordx2 v[72:73], v[72:73], off offset:2048
	v_add_co_u32_e32 v44, vcc, s5, v44
	v_mul_f32_e32 v0, 0xbfb8aa3b, v52
	s_nop 0
	v_addc_co_u32_e32 v45, vcc, 0, v45, vcc
	global_load_dwordx2 v[44:45], v[44:45], off
	v_exp_f32_e32 v0, v0
	s_waitcnt vmcnt(2)
	v_pk_mul_f32 v[42:43], v[76:77], v[42:43]
	v_and_b32_e32 v77, 0xffff0000, v6
	v_lshlrev_b32_e32 v76, 16, v6
	s_waitcnt vmcnt(1)
	v_pk_mul_f32 v[72:73], v[72:73], v[76:77]
	v_add_f32_e32 v0, 1.0, v0
	v_pk_fma_f32 v[42:43], v[60:61], v[42:43], v[72:73] op_sel_hi:[0,1,1]
	v_and_b32_e32 v73, 0xffff0000, v2
	v_lshlrev_b32_e32 v72, 16, v2
	v_rcp_f32_e32 v68, v0
	s_waitcnt vmcnt(0)
	v_pk_mul_f32 v[44:45], v[44:45], v[72:73]
	v_mul_f32_e32 v0, 0xbfb8aa3b, v53
	v_pk_fma_f32 v[72:73], v[58:59], v[44:45], v[42:43] op_sel_hi:[0,1,1]
	global_load_dwordx4 v[42:45], v[64:65], off offset:16
	global_load_dwordx4 v[80:83], v[64:65], off
	v_exp_f32_e32 v0, v0
	s_waitcnt vmcnt(0)
	v_pk_add_f32 v[64:65], v[80:81], v[72:73]
	v_add_f32_e32 v0, 1.0, v0
	v_rcp_f32_e32 v69, v0
	v_add_u32_e32 v0, 0xb02, v62
	v_pk_mul_f32 v[52:53], v[52:53], v[68:69]
	v_and_b32_e32 v69, 0xffff0000, v23
	v_lshlrev_b32_e32 v68, 16, v23
	v_pk_mul_f32 v[22:23], v[50:51], v[68:69]
	v_and_b32_e32 v51, 0xffff0000, v19
	v_lshlrev_b32_e32 v50, 16, v19
	v_pk_mul_f32 v[18:19], v[54:55], v[50:51]
	v_pk_mul_f32 v[52:53], v[64:65], v[52:53]
	v_pk_fma_f32 v[18:19], v[60:61], v[22:23], v[18:19] op_sel_hi:[0,1,1]
	v_and_b32_e32 v23, 0xffff0000, v15
	v_lshlrev_b32_e32 v22, 16, v15
	v_pk_mul_f32 v[14:15], v[70:71], v[22:23]
	v_lshl_add_u64 v[64:65], v[0:1], 2, s[62:63]
	v_pk_fma_f32 v[14:15], v[58:59], v[14:15], v[18:19] op_sel_hi:[0,1,1]
	v_and_b32_e32 v19, 0xffff0000, v11
	v_lshlrev_b32_e32 v18, 16, v11
	v_pk_mul_f32 v[10:11], v[78:79], v[18:19]
	v_add_co_u32_e32 v18, vcc, s4, v64
	v_and_b32_e32 v23, 0xffff0000, v7
	s_nop 0
	v_addc_co_u32_e32 v19, vcc, 0, v65, vcc
	global_load_dwordx2 v[18:19], v[18:19], off offset:2048
	v_lshlrev_b32_e32 v22, 16, v7
	v_pk_add_f32 v[14:15], v[74:75], v[14:15]
	s_waitcnt vmcnt(0)
; __device__ __forceinline__ unsigned cvtpk(float lo, float hi) { f32x2 v = {lo, hi}; bf16x2_t b = __builtin_convertvector(v, bf16x2_t); return __builtin_bit_cast(unsigned, b); }
; __device__ __forceinline__ float bf2f(unsigned short b) { return __uint_as_float((unsigned)b << 16); }
; __device__ __forceinline__ float fast_exp2(float x) { return __builtin_amdgcn_exp2f(x); }
; __device__ __forceinline__ float fast_rcp(float x) { return __builtin_amdgcn_rcpf(x); }
; __device__ __forceinline__ void ffn_fixup(const Params& P, int layer) {
;     ...
;         for (int k = 0; k < 8; ++k) {
;             const int cg_ = col + k, cv_ = DFF + col + k;
;             const float gt = cw[cg_] * bf2f(ug[k]) * fu + cw[NUP + cg_] * bf2f(mg[k]) + cw[2 * NUP + cg_] * bf2f(dg[k]) * fd + cb[cg_];
;             const float vl = cw[cv_] * bf2f(uv[k]) * fu + cw[NUP + cv_] * bf2f(mv[k]) + cw[2 * NUP + cv_] * bf2f(dv[k]) * fd + cb[cv_];
;             res[k] = gt * fast_rcp(1.f + fast_exp2(-LOG2E * gt)) * vl;
;         }
;         u32x4 w; w.x = cvtpk(res[0], res[1]); w.y = cvtpk(res[2], res[3]); w.z = cvtpk(res[4], res[5]); w.w = cvtpk(res[6], res[7]);
;         *(u32x4*)(ACT + (size_t)(chunk * 64 + (e ? 63 : 0)) * DFF + col) = w;
;     }
	v_pk_mul_f32 v[6:7], v[18:19], v[22:23]
	s_nop 0
	v_pk_fma_f32 v[6:7], v[60:61], v[10:11], v[6:7] op_sel_hi:[0,1,1]
	v_add_co_u32_e32 v10, vcc, s5, v64
	v_mul_f32_e32 v0, 0xbfb8aa3b, v14
	s_nop 0
	v_addc_co_u32_e32 v11, vcc, 0, v65, vcc
	global_load_dwordx2 v[10:11], v[10:11], off
	v_exp_f32_e32 v0, v0
	v_and_b32_e32 v19, 0xffff0000, v3
	v_lshlrev_b32_e32 v18, 16, v3
	v_add_f32_e32 v0, 1.0, v0
	v_rcp_f32_e32 v2, v0
	v_mul_f32_e32 v0, 0xbfb8aa3b, v15
	v_exp_f32_e32 v0, v0
	s_waitcnt vmcnt(0)
	v_pk_mul_f32 v[10:11], v[10:11], v[18:19]
	v_add_f32_e32 v0, 1.0, v0
	v_rcp_f32_e32 v3, v0
	v_pk_fma_f32 v[6:7], v[58:59], v[10:11], v[6:7] op_sel_hi:[0,1,1]
	v_pk_add_f32 v[6:7], v[82:83], v[6:7]
	v_add_u32_e32 v0, 0xb04, v62
	v_pk_mul_f32 v[2:3], v[14:15], v[2:3]
	v_and_b32_e32 v11, 0xffff0000, v24
	v_pk_mul_f32 v[2:3], v[6:7], v[2:3]
	v_lshl_add_u64 v[6:7], v[0:1], 2, s[62:63]
	v_add_co_u32_e32 v22, vcc, s4, v6
	v_lshlrev_b32_e32 v10, 16, v24
	s_nop 0
	v_addc_co_u32_e32 v23, vcc, 0, v7, vcc
	global_load_dwordx2 v[22:23], v[22:23], off offset:2048
	v_add_co_u32_e32 v6, vcc, s5, v6
	v_and_b32_e32 v15, 0xffff0000, v20
	s_nop 0
	v_addc_co_u32_e32 v7, vcc, 0, v7, vcc
	global_load_dwordx2 v[6:7], v[6:7], off
	v_lshlrev_b32_e32 v14, 16, v20
	v_pk_mul_f32 v[10:11], v[26:27], v[10:11]
	v_pk_mul_f32 v[14:15], v[30:31], v[14:15]
	v_and_b32_e32 v19, 0xffff0000, v12
	v_pk_fma_f32 v[10:11], v[60:61], v[10:11], v[14:15] op_sel_hi:[0,1,1]
	v_and_b32_e32 v15, 0xffff0000, v16
	v_lshlrev_b32_e32 v14, 16, v16
	v_pk_mul_f32 v[14:15], v[34:35], v[14:15]
	v_lshlrev_b32_e32 v18, 16, v12
	v_pk_fma_f32 v[10:11], v[58:59], v[14:15], v[10:11] op_sel_hi:[0,1,1]
	v_pk_add_f32 v[10:11], v[38:39], v[10:11]
	v_and_b32_e32 v27, 0xffff0000, v8
	v_mul_f32_e32 v0, 0xbfb8aa3b, v10
	v_exp_f32_e32 v0, v0
	v_lshlrev_b32_e32 v26, 16, v8
	v_pk_mul_f32 v[18:19], v[46:47], v[18:19]
	v_add_f32_e32 v0, 1.0, v0
	v_rcp_f32_e32 v14, v0
	v_mul_f32_e32 v0, 0xbfb8aa3b, v11
	v_exp_f32_e32 v0, v0
	s_waitcnt vmcnt(1)
	v_pk_mul_f32 v[22:23], v[22:23], v[26:27]
	v_add_f32_e32 v0, 1.0, v0
	v_rcp_f32_e32 v15, v0
	v_pk_fma_f32 v[18:19], v[60:61], v[18:19], v[22:23] op_sel_hi:[0,1,1]
	v_and_b32_e32 v23, 0xffff0000, v4
	v_lshlrev_b32_e32 v22, 16, v4
	s_waitcnt vmcnt(0)
	v_pk_mul_f32 v[6:7], v[6:7], v[22:23]
	v_pk_mul_f32 v[10:11], v[10:11], v[14:15]
	v_pk_fma_f32 v[6:7], v[58:59], v[6:7], v[18:19] op_sel_hi:[0,1,1]
	v_pk_add_f32 v[6:7], v[42:43], v[6:7]
	v_and_b32_e32 v19, 0xffff0000, v21
	v_pk_mul_f32 v[6:7], v[6:7], v[10:11]
	v_and_b32_e32 v11, 0xffff0000, v25
	v_lshlrev_b32_e32 v10, 16, v25
	v_lshlrev_b32_e32 v18, 16, v21
	v_pk_mul_f32 v[10:11], v[28:29], v[10:11]
	v_pk_mul_f32 v[18:19], v[32:33], v[18:19]
	v_add_u32_e32 v0, 0xb06, v62
	v_pk_fma_f32 v[10:11], v[60:61], v[10:11], v[18:19] op_sel_hi:[0,1,1]
	v_and_b32_e32 v19, 0xffff0000, v17
	v_lshlrev_b32_e32 v18, 16, v17
	v_pk_mul_f32 v[16:17], v[36:37], v[18:19]
	v_lshl_add_u64 v[14:15], v[0:1], 2, s[62:63]
	v_pk_fma_f32 v[10:11], v[58:59], v[16:17], v[10:11] op_sel_hi:[0,1,1]
	v_and_b32_e32 v17, 0xffff0000, v13
	v_lshlrev_b32_e32 v16, 16, v13
	v_pk_mul_f32 v[12:13], v[48:49], v[16:17]
	v_add_co_u32_e32 v16, vcc, s4, v14
	v_and_b32_e32 v19, 0xffff0000, v9
	s_nop 0
	v_addc_co_u32_e32 v17, vcc, 0, v15, vcc
	global_load_dwordx2 v[16:17], v[16:17], off offset:2048
	v_lshlrev_b32_e32 v18, 16, v9
	v_pk_add_f32 v[10:11], v[40:41], v[10:11]
	s_movk_i32 s4, 0x1600
	v_mul_f32_e32 v0, 0xbfb8aa3b, v10
	v_exp_f32_e32 v0, v0
	v_cvt_pk_bf16_f32 v6, v6, v7
	v_add_f32_e32 v0, 1.0, v0
	v_rcp_f32_e32 v4, v0
	v_mul_f32_e32 v0, 0xbfb8aa3b, v11
	v_exp_f32_e32 v0, v0
	s_waitcnt vmcnt(0)
	v_pk_mul_f32 v[8:9], v[16:17], v[18:19]
	s_nop 0
	v_pk_fma_f32 v[8:9], v[60:61], v[12:13], v[8:9] op_sel_hi:[0,1,1]
	v_add_co_u32_e32 v12, vcc, s5, v14
	v_add_f32_e32 v0, 1.0, v0
	s_nop 0
	v_addc_co_u32_e32 v13, vcc, 0, v15, vcc
	global_load_dwordx2 v[12:13], v[12:13], off
	v_and_b32_e32 v15, 0xffff0000, v5
	v_lshlrev_b32_e32 v14, 16, v5
	v_rcp_f32_e32 v5, v0
	v_lshl_or_b32 v0, v66, 6, v67
	v_pk_mul_f32 v[4:5], v[10:11], v[4:5]
	s_waitcnt vmcnt(0)
	v_pk_mul_f32 v[12:13], v[12:13], v[14:15]
	s_nop 0
	v_pk_fma_f32 v[8:9], v[58:59], v[12:13], v[8:9] op_sel_hi:[0,1,1]
	v_pk_add_f32 v[8:9], v[44:45], v[8:9]
	s_nop 0
	v_pk_mul_f32 v[8:9], v[8:9], v[4:5]
	v_cvt_pk_bf16_f32 v5, v2, v3
	v_mov_b64_e32 v[2:3], s[90:91]
	v_mad_i64_i32 v[2:3], s[4:5], v0, s4, v[2:3]
	v_readlane_b32 s4, v252, 7
	v_cvt_pk_bf16_f32 v4, v52, v53
	v_cvt_pk_bf16_f32 v7, v8, v9
	v_add_u32_e32 v61, s4, v61
	v_readlane_b32 s4, v252, 22
	v_lshl_add_u64 v[2:3], v[2:3], 0, v[56:57]
	global_store_dwordx4 v[2:3], v[4:7], off
	v_add_u32_e32 v59, s4, v59
	s_mov_b32 s4, 0x57fff
	v_cmp_lt_i32_e32 vcc, s4, v61
	s_or_b64 s[10:11], vcc, s[10:11]
	s_andn2_b64 exec, exec, s[10:11]
	s_cbranch_execz .LBB0_866
